# v36 plus P6 LN1 epilogue: the sixteen 1/sqrtf expansions per lane replaced by v_rsq_f32 (as the baseline's other LayerNorms use), -400 VALU per wave
# speedup vs baseline: 1.0037x; 1.0037x over previous
.LBB0_496:
	s_or_b64 exec, exec, s[4:5]
	v_lshl_add_u64 v[162:163], v[210:211], 2, s[28:29]
	v_add_co_u32_e32 v166, vcc, 0x4000, v162
	s_waitcnt lgkmcnt(0)
	s_barrier
	s_mov_b64 s[0:1], 0x4000
	s_waitcnt lgkmcnt(4)
	v_addc_co_u32_e32 v167, vcc, 0, v163, vcc
	v_lshl_add_u64 v[164:165], v[162:163], 0, s[0:1]
	global_load_dwordx4 v[194:197], v[166:167], off
	global_load_dwordx4 v[178:181], v[164:165], off offset:528
	global_load_dwordx4 v[200:203], v[164:165], off offset:16
	global_load_dwordx4 v[204:207], v[164:165], off offset:512
	v_lshl_add_u32 v164, v1, 5, 0
	v_add_f32_e32 v192, v222, v223
	v_add_f32_e32 v187, v220, v221
	ds_read_b128 v[220:223], v164 offset:24576
	ds_read_b64 v[208:209], v164 offset:24592
	v_mov_b32_e32 v188, 0x3a800000
	s_mov_b32 s3, 0xf800000
	s_mov_b64 s[0:1], 0x3000
	s_waitcnt lgkmcnt(1)
	v_mul_f32_e32 v213, 0x3a800000, v220
	v_mov_b32_e32 v212, v221
	v_mov_b32_e32 v189, v213
	v_pk_mul_f32 v[190:191], v[212:213], v[188:189]
	v_lshl_add_u64 v[166:167], v[162:163], 0, s[0:1]
	v_sub_f32_e32 v164, v190, v191
	v_add_f32_e32 v164, 0x3727c5ac, v164
	v_rsq_f32_e32 v232, v164
	v_add_co_u32_e32 v162, vcc, 0x3000, v162
	s_nop 0
	s_nop 0
	v_addc_co_u32_e32 v163, vcc, 0, v163, vcc
	global_load_dwordx4 v[174:177], v[162:163], off
	s_nop 0
	global_load_dwordx4 v[162:165], v[166:167], off offset:528
	v_mov_b32_e32 v198, 0x260
	v_pk_add_f32 v[184:185], v[182:183], v[184:185]
	v_add_f32_e32 v212, v213, v213
	v_fmamk_f32 v159, v220, 0xba800000, v159
	v_fmac_f32_e32 v158, 0xba800000, v220
	global_load_dwordx4 v[170:173], v[166:167], off offset:16
	s_nop 0
	global_load_dwordx4 v[166:169], v[166:167], off offset:512
	v_fmamk_f32 v153, v220, 0xba800000, v153
	v_fmamk_f32 v152, v220, 0xba800000, v152
	s_mov_b32 s8, 0x3a800000
	v_mov_b32_e32 v216, v232
	v_mul_f32_e32 v182, v216, v216
	v_mul_f32_e32 v191, v191, v216
	v_mov_b32_e32 v190, 2.0
	v_fma_f32 v193, v223, v182, v192
	v_pk_mul_f32 v[182:183], v[216:217], v[190:191] op_sel_hi:[0,1]
	s_waitcnt lgkmcnt(0)
	v_mov_b32_e32 v186, v208
	v_pk_mul_f32 v[182:183], v[186:187], v[182:183]
	v_pk_mul_f32 v[212:213], v[212:213], v[216:217] op_sel_hi:[1,0]
	v_add_f32_e32 v183, v193, v183
	v_add_f32_e32 v186, v182, v183
	v_mul_f32_e32 v182, v216, v212
	v_mul_f32_e32 v189, v222, v216
	v_mul_f32_e32 v191, v209, v182
	v_pk_mul_f32 v[158:159], v[158:159], v[216:217] op_sel_hi:[1,0]
	v_pk_mul_f32 v[152:153], v[152:153], v[216:217] op_sel_hi:[1,0]
	v_add_f32_e32 v193, v218, v219
	v_pk_fma_f32 v[226:227], v[38:39], v[158:159], v[46:47]
	v_fmamk_f32 v157, v220, 0xba800000, v157
	v_fmamk_f32 v156, v220, 0xba800000, v156
	v_fmamk_f32 v151, v220, 0xba800000, v151
	s_waitcnt vmcnt(5)
	v_pk_add_f32 v[158:159], v[200:201], 1.0 op_sel_hi:[1,0]
	v_pk_fma_f32 v[200:201], v[32:33], v[152:153], v[36:37]
	s_waitcnt vmcnt(4)
	v_pk_add_f32 v[152:153], v[204:205], 1.0 op_sel_hi:[1,0]
	v_sub_f32_e32 v204, v186, v191
	v_add_f32_e32 v205, v189, v193
	v_pk_fma_f32 v[204:205], v[184:185], v[212:213], v[204:205] neg_lo:[1,0,0] neg_hi:[1,0,0]
	v_fmac_f32_e32 v150, 0xba800000, v220
	v_pk_mul_f32 v[204:205], v[204:205], s[8:9] op_sel_hi:[1,0]
	v_fmamk_f32 v149, v220, 0xba800000, v149
	v_fma_f32 v186, -v205, v205, v204
	v_add_f32_e32 v186, 0x3727c5ac, v186
	v_rsq_f32_e32 v232, v186
	v_fmamk_f32 v148, v220, 0xba800000, v148
	v_pk_mul_f32 v[156:157], v[156:157], v[216:217] op_sel_hi:[1,0]
	v_pk_mul_f32 v[150:151], v[150:151], v[216:217] op_sel_hi:[1,0]
	v_pk_mul_f32 v[148:149], v[148:149], v[216:217] op_sel_hi:[1,0]
	v_pk_fma_f32 v[228:229], v[28:29], v[156:157], v[44:45]
	v_pk_add_f32 v[156:157], v[202:203], 1.0 op_sel_hi:[1,0]
	v_pk_fma_f32 v[202:203], v[30:31], v[150:151], v[34:35]
	v_pk_add_f32 v[150:151], v[206:207], 1.0 op_sel_hi:[1,0]
	v_pk_fma_f32 v[206:207], v[20:21], v[148:149], v[24:25]
	v_fmamk_f32 v147, v220, 0xba800000, v147
	v_fmac_f32_e32 v146, 0xba800000, v220
	v_pk_mul_f32 v[146:147], v[146:147], v[216:217] op_sel_hi:[1,0]
	v_pk_fma_f32 v[212:213], v[18:19], v[146:147], v[22:23]
	v_pk_add_f32 v[146:147], v[180:181], 1.0 op_sel_hi:[1,0]
	v_fmamk_f32 v161, v220, 0xba800000, v161
	v_fmamk_f32 v160, v220, 0xba800000, v160
	v_pk_mul_f32 v[160:161], v[160:161], v[216:217] op_sel_hi:[1,0]
	v_add_u32_e32 v182, s26, v1
	v_pk_add_f32 v[148:149], v[178:179], 1.0 op_sel_hi:[1,0]
	v_pk_fma_f32 v[224:225], v[40:41], v[160:161], v[48:49]
	v_fmamk_f32 v155, v220, 0xba800000, v155
	v_fmac_f32_e32 v154, 0xba800000, v220
	v_ashrrev_i32_e32 v183, 31, v182
	v_pk_mul_f32 v[154:155], v[154:155], v[216:217] op_sel_hi:[1,0]
	v_mov_b32_e32 v186, v232
	v_sub_f32_e32 v179, v225, v205
	v_sub_f32_e32 v178, v224, v205
	v_sub_f32_e32 v181, v227, v205
	v_sub_f32_e32 v180, v226, v205
	v_lshlrev_b64 v[222:223], 11, v[182:183]
	v_pk_add_f32 v[160:161], v[196:197], 1.0 op_sel_hi:[1,0]
	v_pk_add_f32 v[182:183], v[194:195], 1.0 op_sel_hi:[1,0]
	v_pk_fma_f32 v[230:231], v[26:27], v[154:155], v[42:43]
	v_pk_mul_f32 v[180:181], v[180:181], v[186:187] op_sel_hi:[1,0]
	v_pk_mul_f32 v[178:179], v[178:179], v[186:187] op_sel_hi:[1,0]
	v_lshlrev_b64 v[154:155], 1, v[210:211]
	s_waitcnt vmcnt(3)
	v_pk_fma_f32 v[210:211], v[160:161], v[178:179], v[176:177]
	v_pk_fma_f32 v[178:179], v[182:183], v[180:181], v[174:175]
	v_sub_f32_e32 v181, v229, v205
	v_sub_f32_e32 v180, v228, v205
	v_sub_f32_e32 v217, v231, v205
	v_sub_f32_e32 v216, v230, v205
	v_pk_mul_f32 v[216:217], v[216:217], v[186:187] op_sel_hi:[1,0]
	v_pk_mul_f32 v[180:181], v[180:181], v[186:187] op_sel_hi:[1,0]
	v_lshl_add_u64 v[194:195], s[84:85], 0, v[222:223]
	s_waitcnt vmcnt(1)
	v_pk_fma_f32 v[218:219], v[156:157], v[180:181], v[172:173]
	v_pk_fma_f32 v[180:181], v[158:159], v[216:217], v[170:171]
	v_cvt_pk_bf16_f32 v208, v226, v227
	v_cvt_pk_bf16_f32 v209, v224, v225
	v_lshl_add_u64 v[194:195], v[194:195], 0, v[154:155]
	v_lshl_add_u64 v[196:197], s[66:67], 0, v[222:223]
	v_cvt_pk_bf16_f32 v178, v178, v179
	v_cvt_pk_bf16_f32 v179, v210, v211
	v_cvt_pk_bf16_f32 v210, v230, v231
	v_cvt_pk_bf16_f32 v211, v228, v229
	v_cvt_pk_bf16_f32 v180, v180, v181
	v_cvt_pk_bf16_f32 v181, v218, v219
	v_lshl_add_u64 v[196:197], v[196:197], 0, v[154:155]
	global_store_dwordx4 v[194:195], v[208:211], off
	global_store_dwordx4 v[196:197], v[178:181], off
	v_or_b32_e32 v191, 16, v1
	v_lshl_add_u32 v189, v191, 5, 0
	v_cvt_pk_bf16_f32 v178, v202, v203
	v_cvt_pk_bf16_f32 v179, v200, v201
	v_sub_f32_e32 v181, v201, v205
	v_sub_f32_e32 v180, v200, v205
	v_sub_f32_e32 v201, v203, v205
	v_sub_f32_e32 v200, v202, v205
	v_pk_mul_f32 v[200:201], v[200:201], v[186:187] op_sel_hi:[1,0]
	v_pk_mul_f32 v[180:181], v[180:181], v[186:187] op_sel_hi:[1,0]
	s_waitcnt vmcnt(2)
	v_pk_fma_f32 v[200:201], v[152:153], v[200:201], v[166:167]
	v_pk_fma_f32 v[180:181], v[150:151], v[180:181], v[168:169]
	v_cvt_pk_bf16_f32 v200, v200, v201
	v_sub_f32_e32 v203, v207, v205
	v_cvt_pk_bf16_f32 v201, v180, v181
	v_cvt_pk_bf16_f32 v180, v212, v213
	v_cvt_pk_bf16_f32 v181, v206, v207
	v_sub_f32_e32 v202, v206, v205
	v_sub_f32_e32 v207, v213, v205
	v_sub_f32_e32 v206, v212, v205
	v_pk_mul_f32 v[204:205], v[206:207], v[186:187] op_sel_hi:[1,0]
	v_pk_mul_f32 v[202:203], v[202:203], v[186:187] op_sel_hi:[1,0]
	s_nop 0
	v_pk_fma_f32 v[206:207], v[146:147], v[202:203], v[164:165]
	v_pk_fma_f32 v[202:203], v[148:149], v[204:205], v[162:163]
	s_nop 0
	v_cvt_pk_bf16_f32 v202, v202, v203
	v_cvt_pk_bf16_f32 v203, v206, v207
	global_store_dwordx4 v[194:195], v[178:181], off offset:256
	global_store_dwordx4 v[196:197], v[200:203], off offset:256
	ds_read_b128 v[178:181], v189 offset:24576
	ds_read_b64 v[194:195], v189 offset:24592
	v_add_u32_e32 v202, s26, v191
	v_ashrrev_i32_e32 v203, 31, v202
	v_lshlrev_b64 v[202:203], 11, v[202:203]
	s_waitcnt lgkmcnt(1)
	v_mul_f32_e32 v197, 0x3a800000, v178
	v_mov_b32_e32 v196, v179
	v_mov_b32_e32 v189, v197
	v_pk_mul_f32 v[200:201], v[196:197], v[188:189]
	v_fmamk_f32 v145, v178, 0xba800000, v145
	v_sub_f32_e32 v179, v200, v201
	v_add_f32_e32 v179, 0x3727c5ac, v179
	v_rsq_f32_e32 v232, v179
	v_fmamk_f32 v144, v178, 0xba800000, v144
	v_fmamk_f32 v143, v178, 0xba800000, v143
	v_fmac_f32_e32 v142, 0xba800000, v178
	v_fmamk_f32 v139, v178, 0xba800000, v139
	v_fmac_f32_e32 v138, 0xba800000, v178
	v_fmamk_f32 v141, v178, 0xba800000, v141
	v_fmamk_f32 v140, v178, 0xba800000, v140
	v_fmamk_f32 v137, v178, 0xba800000, v137
	v_fmamk_f32 v136, v178, 0xba800000, v136
	v_fmamk_f32 v135, v178, 0xba800000, v135
	v_fmac_f32_e32 v134, 0xba800000, v178
	v_fmamk_f32 v133, v178, 0xba800000, v133
	v_fmamk_f32 v132, v178, 0xba800000, v132
	v_mov_b32_e32 v200, v232
	v_mul_f32_e32 v179, v180, v200
	v_mul_f32_e32 v180, v200, v200
	v_mul_f32_e32 v191, v201, v200
	v_fma_f32 v189, v181, v180, v192
	v_pk_mul_f32 v[180:181], v[200:201], v[190:191] op_sel_hi:[0,1]
	s_waitcnt lgkmcnt(0)
	v_mov_b32_e32 v186, v194
	v_pk_mul_f32 v[180:181], v[186:187], v[180:181]
	v_add_f32_e32 v196, v197, v197
	v_add_f32_e32 v181, v189, v181
	v_add_f32_e32 v186, v180, v181
	v_pk_mul_f32 v[180:181], v[196:197], v[200:201] op_sel_hi:[1,0]
	v_pk_mul_f32 v[142:143], v[142:143], v[200:201] op_sel_hi:[1,0]
	v_mul_f32_e32 v189, v200, v180
	v_mul_f32_e32 v189, v195, v189
	v_sub_f32_e32 v194, v186, v189
	v_add_f32_e32 v195, v179, v193
	v_pk_fma_f32 v[180:181], v[184:185], v[180:181], v[194:195] neg_lo:[1,0,0] neg_hi:[1,0,0]
	v_lshl_add_u64 v[194:195], s[84:85], 0, v[202:203]
	v_pk_mul_f32 v[180:181], v[180:181], s[8:9] op_sel_hi:[1,0]
	v_lshl_add_u64 v[204:205], v[194:195], 0, v[154:155]
	v_fma_f32 v179, -v181, v181, v180
	v_add_f32_e32 v179, 0x3727c5ac, v179
	v_rsq_f32_e32 v232, v179
	v_lshl_add_u64 v[194:195], s[66:67], 0, v[202:203]
	v_lshl_add_u64 v[202:203], v[194:195], 0, v[154:155]
	v_pk_mul_f32 v[144:145], v[144:145], v[200:201] op_sel_hi:[1,0]
	v_pk_mul_f32 v[138:139], v[138:139], v[200:201] op_sel_hi:[1,0]
	v_pk_fma_f32 v[144:145], v[40:41], v[144:145], v[48:49]
	v_pk_fma_f32 v[138:139], v[26:27], v[138:139], v[42:43]
	v_pk_mul_f32 v[140:141], v[140:141], v[200:201] op_sel_hi:[1,0]
	v_pk_mul_f32 v[134:135], v[134:135], v[200:201] op_sel_hi:[1,0]
	v_pk_fma_f32 v[140:141], v[28:29], v[140:141], v[44:45]
	v_pk_mul_f32 v[136:137], v[136:137], v[200:201] op_sel_hi:[1,0]
	v_pk_fma_f32 v[136:137], v[32:33], v[136:137], v[36:37]
	v_fmamk_f32 v131, v178, 0xba800000, v131
	v_fmac_f32_e32 v130, 0xba800000, v178
	v_pk_fma_f32 v[194:195], v[38:39], v[142:143], v[46:47]
	v_mov_b32_e32 v180, v232
	v_cvt_pk_bf16_f32 v142, v194, v195
	v_cvt_pk_bf16_f32 v143, v144, v145
	v_sub_f32_e32 v145, v145, v181
	v_sub_f32_e32 v144, v144, v181
	v_sub_f32_e32 v195, v195, v181
	v_sub_f32_e32 v194, v194, v181
	v_pk_mul_f32 v[194:195], v[194:195], v[180:181] op_sel_hi:[1,0]
	v_pk_mul_f32 v[144:145], v[144:145], v[180:181] op_sel_hi:[1,0]
	v_pk_fma_f32 v[194:195], v[182:183], v[194:195], v[174:175]
	v_pk_fma_f32 v[144:145], v[160:161], v[144:145], v[176:177]
	v_cvt_pk_bf16_f32 v194, v194, v195
	v_pk_mul_f32 v[130:131], v[130:131], v[200:201] op_sel_hi:[1,0]
	v_cvt_pk_bf16_f32 v195, v144, v145
	v_cvt_pk_bf16_f32 v144, v138, v139
	v_sub_f32_e32 v139, v139, v181
	v_sub_f32_e32 v138, v138, v181
	v_pk_mul_f32 v[138:139], v[138:139], v[180:181] op_sel_hi:[1,0]
	v_cvt_pk_bf16_f32 v145, v140, v141
	v_sub_f32_e32 v141, v141, v181
	v_sub_f32_e32 v140, v140, v181
	v_pk_fma_f32 v[138:139], v[158:159], v[138:139], v[170:171]
	v_pk_mul_f32 v[140:141], v[140:141], v[180:181] op_sel_hi:[1,0]
	v_cvt_pk_bf16_f32 v196, v138, v139
	v_pk_fma_f32 v[138:139], v[30:31], v[134:135], v[34:35]
	v_pk_fma_f32 v[140:141], v[156:157], v[140:141], v[172:173]
	v_pk_mul_f32 v[132:133], v[132:133], v[200:201] op_sel_hi:[1,0]
	v_cvt_pk_bf16_f32 v197, v140, v141
	global_store_dwordx4 v[204:205], v[142:145], off
	global_store_dwordx4 v[202:203], v[194:197], off
	v_cvt_pk_bf16_f32 v134, v138, v139
	v_cvt_pk_bf16_f32 v135, v136, v137
	v_sub_f32_e32 v137, v137, v181
	v_sub_f32_e32 v136, v136, v181
	v_sub_f32_e32 v139, v139, v181
	v_sub_f32_e32 v138, v138, v181
	v_pk_mul_f32 v[138:139], v[138:139], v[180:181] op_sel_hi:[1,0]
	v_pk_mul_f32 v[136:137], v[136:137], v[180:181] op_sel_hi:[1,0]
	v_pk_fma_f32 v[138:139], v[152:153], v[138:139], v[166:167]
	v_pk_fma_f32 v[136:137], v[150:151], v[136:137], v[168:169]
	v_pk_fma_f32 v[132:133], v[20:21], v[132:133], v[24:25]
	v_pk_fma_f32 v[130:131], v[18:19], v[130:131], v[22:23]
	v_cvt_pk_bf16_f32 v138, v138, v139
	v_cvt_pk_bf16_f32 v139, v136, v137
	v_or_b32_e32 v191, 32, v1
	v_cvt_pk_bf16_f32 v136, v130, v131
	v_cvt_pk_bf16_f32 v137, v132, v133
	v_sub_f32_e32 v133, v133, v181
	v_sub_f32_e32 v132, v132, v181
	v_sub_f32_e32 v131, v131, v181
	v_sub_f32_e32 v130, v130, v181
	v_pk_mul_f32 v[130:131], v[130:131], v[180:181] op_sel_hi:[1,0]
	v_pk_mul_f32 v[132:133], v[132:133], v[180:181] op_sel_hi:[1,0]
	v_pk_fma_f32 v[130:131], v[148:149], v[130:131], v[162:163]
	v_pk_fma_f32 v[132:133], v[146:147], v[132:133], v[164:165]
	v_cvt_pk_bf16_f32 v140, v130, v131
	v_lshl_add_u32 v189, v191, 5, 0
	v_cvt_pk_bf16_f32 v141, v132, v133
	global_store_dwordx4 v[204:205], v[134:137], off offset:256
	global_store_dwordx4 v[202:203], v[138:141], off offset:256
	ds_read_b128 v[130:133], v189 offset:24576
	ds_read_b64 v[134:135], v189 offset:24592
	s_waitcnt lgkmcnt(1)
	v_mul_f32_e32 v137, 0x3a800000, v130
	v_mov_b32_e32 v136, v131
	v_mov_b32_e32 v189, v137
	v_pk_mul_f32 v[138:139], v[136:137], v[188:189]
	s_waitcnt lgkmcnt(0)
	v_mov_b32_e32 v186, v134
	v_sub_f32_e32 v131, v138, v139
	v_add_f32_e32 v131, 0x3727c5ac, v131
	v_rsq_f32_e32 v232, v131
	v_fmamk_f32 v129, v130, 0xba800000, v129
	v_fmamk_f32 v128, v130, 0xba800000, v128
	v_fmamk_f32 v127, v130, 0xba800000, v127
	v_fmac_f32_e32 v126, 0xba800000, v130
	v_fmamk_f32 v123, v130, 0xba800000, v123
	v_fmac_f32_e32 v122, 0xba800000, v130
	v_fmamk_f32 v125, v130, 0xba800000, v125
	v_fmamk_f32 v124, v130, 0xba800000, v124
	v_add_u32_e32 v140, s26, v191
	v_ashrrev_i32_e32 v141, 31, v140
	v_lshlrev_b64 v[140:141], 11, v[140:141]
	v_fmamk_f32 v121, v130, 0xba800000, v121
	v_fmamk_f32 v120, v130, 0xba800000, v120
	v_mov_b32_e32 v138, v232
	v_mul_f32_e32 v131, v132, v138
	v_mul_f32_e32 v132, v138, v138
	v_mul_f32_e32 v191, v139, v138
	v_fma_f32 v136, v133, v132, v192
	v_pk_mul_f32 v[132:133], v[138:139], v[190:191] op_sel_hi:[0,1]
	v_pk_mul_f32 v[132:133], v[186:187], v[132:133]
	v_fmamk_f32 v119, v130, 0xba800000, v119
	v_add_f32_e32 v133, v136, v133
	v_add_f32_e32 v136, v137, v137
	v_add_f32_e32 v134, v132, v133
	v_pk_mul_f32 v[132:133], v[136:137], v[138:139] op_sel_hi:[1,0]
	v_or_b32_e32 v139, 48, v1
	v_mul_f32_e32 v136, v138, v132
	v_mul_f32_e32 v135, v135, v136
	v_sub_f32_e32 v134, v134, v135
	v_add_f32_e32 v135, v131, v193
	v_pk_fma_f32 v[132:133], v[184:185], v[132:133], v[134:135] neg_lo:[1,0,0] neg_hi:[1,0,0]
	v_pk_mul_f32 v[126:127], v[126:127], v[138:139] op_sel_hi:[1,0]
	v_pk_mul_f32 v[136:137], v[132:133], s[8:9] op_sel_hi:[1,0]
	v_pk_mul_f32 v[128:129], v[128:129], v[138:139] op_sel_hi:[1,0]
	v_fma_f32 v131, -v137, v137, v136
	v_add_f32_e32 v131, 0x3727c5ac, v131
	v_rsq_f32_e32 v232, v131
	v_pk_fma_f32 v[128:129], v[40:41], v[128:129], v[48:49]
	v_pk_mul_f32 v[122:123], v[122:123], v[138:139] op_sel_hi:[1,0]
	v_lshl_add_u64 v[132:133], s[84:85], 0, v[140:141]
	v_lshl_add_u64 v[142:143], v[132:133], 0, v[154:155]
	v_lshl_add_u64 v[132:133], s[66:67], 0, v[140:141]
	v_lshl_add_u64 v[140:141], v[132:133], 0, v[154:155]
	v_pk_fma_f32 v[122:123], v[26:27], v[122:123], v[42:43]
	v_pk_mul_f32 v[124:125], v[124:125], v[138:139] op_sel_hi:[1,0]
	v_pk_fma_f32 v[124:125], v[28:29], v[124:125], v[44:45]
	v_fmac_f32_e32 v118, 0xba800000, v130
	v_pk_mul_f32 v[118:119], v[118:119], v[138:139] op_sel_hi:[1,0]
	v_pk_mul_f32 v[120:121], v[120:121], v[138:139] op_sel_hi:[1,0]
	v_fmamk_f32 v117, v130, 0xba800000, v117
	v_mov_b32_e32 v136, v232
	v_pk_fma_f32 v[132:133], v[38:39], v[126:127], v[46:47]
	v_pk_fma_f32 v[120:121], v[32:33], v[120:121], v[36:37]
	v_cvt_pk_bf16_f32 v126, v132, v133
	v_cvt_pk_bf16_f32 v127, v128, v129
	v_sub_f32_e32 v129, v129, v137
	v_sub_f32_e32 v128, v128, v137
	v_sub_f32_e32 v133, v133, v137
	v_sub_f32_e32 v132, v132, v137
	v_pk_mul_f32 v[132:133], v[132:133], v[136:137] op_sel_hi:[1,0]
	v_pk_mul_f32 v[128:129], v[128:129], v[136:137] op_sel_hi:[1,0]
	v_pk_fma_f32 v[132:133], v[182:183], v[132:133], v[174:175]
	v_pk_fma_f32 v[128:129], v[160:161], v[128:129], v[176:177]
	v_cvt_pk_bf16_f32 v132, v132, v133
	v_fmamk_f32 v116, v130, 0xba800000, v116
	v_cvt_pk_bf16_f32 v133, v128, v129
	v_cvt_pk_bf16_f32 v128, v122, v123
	v_sub_f32_e32 v123, v123, v137
	v_sub_f32_e32 v122, v122, v137
	v_pk_mul_f32 v[122:123], v[122:123], v[136:137] op_sel_hi:[1,0]
	v_cvt_pk_bf16_f32 v129, v124, v125
	v_sub_f32_e32 v125, v125, v137
	v_sub_f32_e32 v124, v124, v137
	v_pk_fma_f32 v[122:123], v[158:159], v[122:123], v[170:171]
	v_pk_mul_f32 v[124:125], v[124:125], v[136:137] op_sel_hi:[1,0]
	v_cvt_pk_bf16_f32 v134, v122, v123
	v_pk_fma_f32 v[122:123], v[30:31], v[118:119], v[34:35]
	v_pk_fma_f32 v[124:125], v[156:157], v[124:125], v[172:173]
	v_fmamk_f32 v115, v130, 0xba800000, v115
	v_cvt_pk_bf16_f32 v135, v124, v125
	global_store_dwordx4 v[142:143], v[126:129], off
	global_store_dwordx4 v[140:141], v[132:135], off
	v_cvt_pk_bf16_f32 v118, v122, v123
	v_cvt_pk_bf16_f32 v119, v120, v121
	v_sub_f32_e32 v121, v121, v137
	v_sub_f32_e32 v120, v120, v137
	v_sub_f32_e32 v123, v123, v137
	v_sub_f32_e32 v122, v122, v137
	v_fmac_f32_e32 v114, 0xba800000, v130
	v_pk_mul_f32 v[122:123], v[122:123], v[136:137] op_sel_hi:[1,0]
	v_pk_mul_f32 v[120:121], v[120:121], v[136:137] op_sel_hi:[1,0]
	v_pk_mul_f32 v[114:115], v[114:115], v[138:139] op_sel_hi:[1,0]
	v_pk_mul_f32 v[116:117], v[116:117], v[138:139] op_sel_hi:[1,0]
	v_pk_fma_f32 v[120:121], v[150:151], v[120:121], v[168:169]
	v_pk_fma_f32 v[122:123], v[152:153], v[122:123], v[166:167]
	v_pk_fma_f32 v[116:117], v[20:21], v[116:117], v[24:25]
	v_pk_fma_f32 v[114:115], v[18:19], v[114:115], v[22:23]
	v_cvt_pk_bf16_f32 v122, v122, v123
	v_cvt_pk_bf16_f32 v123, v120, v121
	v_lshl_add_u32 v144, v139, 5, 0
	v_cvt_pk_bf16_f32 v120, v114, v115
	v_cvt_pk_bf16_f32 v121, v116, v117
	v_sub_f32_e32 v117, v117, v137
	v_sub_f32_e32 v116, v116, v137
	v_sub_f32_e32 v115, v115, v137
	v_sub_f32_e32 v114, v114, v137
	v_pk_mul_f32 v[114:115], v[114:115], v[136:137] op_sel_hi:[1,0]
	v_pk_mul_f32 v[116:117], v[116:117], v[136:137] op_sel_hi:[1,0]
	v_pk_fma_f32 v[114:115], v[148:149], v[114:115], v[162:163]
	v_pk_fma_f32 v[116:117], v[146:147], v[116:117], v[164:165]
	v_cvt_pk_bf16_f32 v124, v114, v115
	s_nop 0
	v_cvt_pk_bf16_f32 v125, v116, v117
	global_store_dwordx4 v[142:143], v[118:121], off offset:256
	global_store_dwordx4 v[140:141], v[122:125], off offset:256
	ds_read_b128 v[114:117], v144 offset:24576
	ds_read_b64 v[118:119], v144 offset:24592
	s_waitcnt lgkmcnt(1)
	v_mul_f32_e32 v121, 0x3a800000, v114
	v_mov_b32_e32 v120, v115
	v_mov_b32_e32 v189, v121
	v_pk_mul_f32 v[122:123], v[120:121], v[188:189]
	s_waitcnt lgkmcnt(0)
	v_mov_b32_e32 v186, v118
	v_sub_f32_e32 v115, v122, v123
	v_add_f32_e32 v115, 0x3727c5ac, v115
	v_rsq_f32_e32 v232, v115
	v_fmamk_f32 v113, v114, 0xba800000, v113
	v_fmamk_f32 v112, v114, 0xba800000, v112
	v_fmamk_f32 v111, v114, 0xba800000, v111
	v_fmac_f32_e32 v110, 0xba800000, v114
	v_fmamk_f32 v107, v114, 0xba800000, v107
	v_fmac_f32_e32 v106, 0xba800000, v114
	v_fmamk_f32 v109, v114, 0xba800000, v109
	v_fmamk_f32 v108, v114, 0xba800000, v108
	v_add_u32_e32 v124, s26, v139
	v_ashrrev_i32_e32 v125, 31, v124
	v_lshlrev_b64 v[124:125], 11, v[124:125]
	v_fmamk_f32 v105, v114, 0xba800000, v105
	v_fmamk_f32 v104, v114, 0xba800000, v104
	v_mov_b32_e32 v122, v232
	v_mul_f32_e32 v115, v116, v122
	v_mul_f32_e32 v116, v122, v122
	v_mul_f32_e32 v191, v123, v122
	v_fma_f32 v120, v117, v116, v192
	v_pk_mul_f32 v[116:117], v[122:123], v[190:191] op_sel_hi:[0,1]
	v_pk_mul_f32 v[116:117], v[186:187], v[116:117]
	v_fmamk_f32 v103, v114, 0xba800000, v103
	v_add_f32_e32 v117, v120, v117
	v_add_f32_e32 v120, v121, v121
	v_add_f32_e32 v118, v116, v117
	v_pk_mul_f32 v[116:117], v[120:121], v[122:123] op_sel_hi:[1,0]
	v_add_u32_e32 v123, 0x80, v1
	v_mul_f32_e32 v120, v122, v116
	v_mul_f32_e32 v119, v119, v120
	v_sub_f32_e32 v118, v118, v119
	v_add_f32_e32 v119, v115, v193
	v_pk_fma_f32 v[116:117], v[184:185], v[116:117], v[118:119] neg_lo:[1,0,0] neg_hi:[1,0,0]
	v_pk_mul_f32 v[110:111], v[110:111], v[122:123] op_sel_hi:[1,0]
	v_pk_mul_f32 v[120:121], v[116:117], s[8:9] op_sel_hi:[1,0]
	v_pk_mul_f32 v[112:113], v[112:113], v[122:123] op_sel_hi:[1,0]
	v_fma_f32 v115, -v121, v121, v120
	v_add_f32_e32 v115, 0x3727c5ac, v115
	v_rsq_f32_e32 v232, v115
	v_pk_fma_f32 v[112:113], v[40:41], v[112:113], v[48:49]
	v_pk_mul_f32 v[106:107], v[106:107], v[122:123] op_sel_hi:[1,0]
	v_lshl_add_u64 v[116:117], s[84:85], 0, v[124:125]
	v_lshl_add_u64 v[126:127], v[116:117], 0, v[154:155]
	v_lshl_add_u64 v[116:117], s[66:67], 0, v[124:125]
	v_lshl_add_u64 v[124:125], v[116:117], 0, v[154:155]
	v_pk_fma_f32 v[106:107], v[26:27], v[106:107], v[42:43]
	v_pk_mul_f32 v[108:109], v[108:109], v[122:123] op_sel_hi:[1,0]
	v_pk_fma_f32 v[108:109], v[28:29], v[108:109], v[44:45]
	v_fmac_f32_e32 v102, 0xba800000, v114
	v_pk_mul_f32 v[102:103], v[102:103], v[122:123] op_sel_hi:[1,0]
	v_pk_mul_f32 v[104:105], v[104:105], v[122:123] op_sel_hi:[1,0]
	v_fmamk_f32 v101, v114, 0xba800000, v101
	v_mov_b32_e32 v120, v232
	v_pk_fma_f32 v[116:117], v[38:39], v[110:111], v[46:47]
	v_pk_fma_f32 v[104:105], v[32:33], v[104:105], v[36:37]
	v_cvt_pk_bf16_f32 v110, v116, v117
	v_cvt_pk_bf16_f32 v111, v112, v113
	v_sub_f32_e32 v113, v113, v121
	v_sub_f32_e32 v112, v112, v121
	v_sub_f32_e32 v117, v117, v121
	v_sub_f32_e32 v116, v116, v121
	v_pk_mul_f32 v[116:117], v[116:117], v[120:121] op_sel_hi:[1,0]
	v_pk_mul_f32 v[112:113], v[112:113], v[120:121] op_sel_hi:[1,0]
	v_pk_fma_f32 v[116:117], v[182:183], v[116:117], v[174:175]
	v_pk_fma_f32 v[112:113], v[160:161], v[112:113], v[176:177]
	v_cvt_pk_bf16_f32 v116, v116, v117
	v_fmamk_f32 v100, v114, 0xba800000, v100
	v_cvt_pk_bf16_f32 v117, v112, v113
	v_cvt_pk_bf16_f32 v112, v106, v107
	v_sub_f32_e32 v107, v107, v121
	v_sub_f32_e32 v106, v106, v121
	v_pk_mul_f32 v[106:107], v[106:107], v[120:121] op_sel_hi:[1,0]
	v_cvt_pk_bf16_f32 v113, v108, v109
	v_sub_f32_e32 v109, v109, v121
	v_sub_f32_e32 v108, v108, v121
	v_pk_fma_f32 v[106:107], v[158:159], v[106:107], v[170:171]
	v_pk_mul_f32 v[108:109], v[108:109], v[120:121] op_sel_hi:[1,0]
	v_cvt_pk_bf16_f32 v118, v106, v107
	v_pk_fma_f32 v[106:107], v[30:31], v[102:103], v[34:35]
	v_pk_fma_f32 v[108:109], v[156:157], v[108:109], v[172:173]
	v_fmamk_f32 v99, v114, 0xba800000, v99
	v_cvt_pk_bf16_f32 v119, v108, v109
	global_store_dwordx4 v[126:127], v[110:113], off
	global_store_dwordx4 v[124:125], v[116:119], off
	v_cvt_pk_bf16_f32 v102, v106, v107
	v_cvt_pk_bf16_f32 v103, v104, v105
	v_sub_f32_e32 v105, v105, v121
	v_sub_f32_e32 v104, v104, v121
	v_sub_f32_e32 v107, v107, v121
	v_sub_f32_e32 v106, v106, v121
	v_fmac_f32_e32 v98, 0xba800000, v114
	v_pk_mul_f32 v[106:107], v[106:107], v[120:121] op_sel_hi:[1,0]
	v_pk_mul_f32 v[104:105], v[104:105], v[120:121] op_sel_hi:[1,0]
	v_pk_mul_f32 v[98:99], v[98:99], v[122:123] op_sel_hi:[1,0]
	v_pk_mul_f32 v[100:101], v[100:101], v[122:123] op_sel_hi:[1,0]
	v_pk_fma_f32 v[104:105], v[150:151], v[104:105], v[168:169]
	v_pk_fma_f32 v[106:107], v[152:153], v[106:107], v[166:167]
	v_pk_fma_f32 v[100:101], v[20:21], v[100:101], v[24:25]
	v_pk_fma_f32 v[98:99], v[18:19], v[98:99], v[22:23]
	v_cvt_pk_bf16_f32 v106, v106, v107
	v_cvt_pk_bf16_f32 v107, v104, v105
	v_lshl_add_u32 v128, v123, 5, 0
	v_cvt_pk_bf16_f32 v104, v98, v99
	v_cvt_pk_bf16_f32 v105, v100, v101
	v_sub_f32_e32 v101, v101, v121
	v_sub_f32_e32 v100, v100, v121
	v_sub_f32_e32 v99, v99, v121
	v_sub_f32_e32 v98, v98, v121
	v_pk_mul_f32 v[98:99], v[98:99], v[120:121] op_sel_hi:[1,0]
	v_pk_mul_f32 v[100:101], v[100:101], v[120:121] op_sel_hi:[1,0]
	v_pk_fma_f32 v[98:99], v[148:149], v[98:99], v[162:163]
	v_pk_fma_f32 v[100:101], v[146:147], v[100:101], v[164:165]
	v_cvt_pk_bf16_f32 v108, v98, v99
	s_nop 0
	v_cvt_pk_bf16_f32 v109, v100, v101
	global_store_dwordx4 v[126:127], v[102:105], off offset:256
	global_store_dwordx4 v[124:125], v[106:109], off offset:256
	ds_read_b128 v[98:101], v128 offset:24576
	ds_read_b64 v[102:103], v128 offset:24592
	s_waitcnt lgkmcnt(1)
	v_mul_f32_e32 v105, 0x3a800000, v98
	v_mov_b32_e32 v104, v99
	v_mov_b32_e32 v189, v105
	v_pk_mul_f32 v[106:107], v[104:105], v[188:189]
	s_waitcnt lgkmcnt(0)
	v_mov_b32_e32 v186, v102
	v_sub_f32_e32 v99, v106, v107
	v_add_f32_e32 v99, 0x3727c5ac, v99
	v_rsq_f32_e32 v232, v99
	v_fmamk_f32 v97, v98, 0xba800000, v97
	v_fmamk_f32 v96, v98, 0xba800000, v96
	v_fmamk_f32 v95, v98, 0xba800000, v95
	v_fmac_f32_e32 v94, 0xba800000, v98
	v_fmamk_f32 v91, v98, 0xba800000, v91
	v_fmac_f32_e32 v90, 0xba800000, v98
	v_fmamk_f32 v93, v98, 0xba800000, v93
	v_fmamk_f32 v92, v98, 0xba800000, v92
	v_add_u32_e32 v108, s26, v123
	v_ashrrev_i32_e32 v109, 31, v108
	v_lshlrev_b64 v[108:109], 11, v[108:109]
	v_fmamk_f32 v89, v98, 0xba800000, v89
	v_fmamk_f32 v88, v98, 0xba800000, v88
	v_mov_b32_e32 v106, v232
	v_mul_f32_e32 v99, v100, v106
	v_mul_f32_e32 v100, v106, v106
	v_mul_f32_e32 v191, v107, v106
	v_fma_f32 v104, v101, v100, v192
	v_pk_mul_f32 v[100:101], v[106:107], v[190:191] op_sel_hi:[0,1]
	v_pk_mul_f32 v[100:101], v[186:187], v[100:101]
	v_fmamk_f32 v87, v98, 0xba800000, v87
	v_add_f32_e32 v101, v104, v101
	v_add_f32_e32 v104, v105, v105
	v_add_f32_e32 v102, v100, v101
	v_pk_mul_f32 v[100:101], v[104:105], v[106:107] op_sel_hi:[1,0]
	v_add_u32_e32 v107, 0x90, v1
	v_mul_f32_e32 v104, v106, v100
	v_mul_f32_e32 v103, v103, v104
	v_sub_f32_e32 v102, v102, v103
	v_add_f32_e32 v103, v99, v193
	v_pk_fma_f32 v[100:101], v[184:185], v[100:101], v[102:103] neg_lo:[1,0,0] neg_hi:[1,0,0]
	v_pk_mul_f32 v[94:95], v[94:95], v[106:107] op_sel_hi:[1,0]
	v_pk_mul_f32 v[104:105], v[100:101], s[8:9] op_sel_hi:[1,0]
	v_pk_mul_f32 v[96:97], v[96:97], v[106:107] op_sel_hi:[1,0]
	v_fma_f32 v99, -v105, v105, v104
	v_add_f32_e32 v99, 0x3727c5ac, v99
	v_rsq_f32_e32 v232, v99
	v_pk_fma_f32 v[96:97], v[40:41], v[96:97], v[48:49]
	v_pk_mul_f32 v[90:91], v[90:91], v[106:107] op_sel_hi:[1,0]
	v_lshl_add_u64 v[100:101], s[84:85], 0, v[108:109]
	v_lshl_add_u64 v[110:111], v[100:101], 0, v[154:155]
	v_lshl_add_u64 v[100:101], s[66:67], 0, v[108:109]
	v_lshl_add_u64 v[108:109], v[100:101], 0, v[154:155]
	v_pk_fma_f32 v[90:91], v[26:27], v[90:91], v[42:43]
	v_pk_mul_f32 v[92:93], v[92:93], v[106:107] op_sel_hi:[1,0]
	v_pk_fma_f32 v[92:93], v[28:29], v[92:93], v[44:45]
	v_fmac_f32_e32 v86, 0xba800000, v98
	v_pk_mul_f32 v[86:87], v[86:87], v[106:107] op_sel_hi:[1,0]
	v_pk_mul_f32 v[88:89], v[88:89], v[106:107] op_sel_hi:[1,0]
	v_fmamk_f32 v85, v98, 0xba800000, v85
	v_mov_b32_e32 v104, v232
	v_pk_fma_f32 v[100:101], v[38:39], v[94:95], v[46:47]
	v_pk_fma_f32 v[88:89], v[32:33], v[88:89], v[36:37]
	v_cvt_pk_bf16_f32 v94, v100, v101
	v_cvt_pk_bf16_f32 v95, v96, v97
	v_sub_f32_e32 v97, v97, v105
	v_sub_f32_e32 v96, v96, v105
	v_sub_f32_e32 v101, v101, v105
	v_sub_f32_e32 v100, v100, v105
	v_pk_mul_f32 v[100:101], v[100:101], v[104:105] op_sel_hi:[1,0]
	v_pk_mul_f32 v[96:97], v[96:97], v[104:105] op_sel_hi:[1,0]
	v_pk_fma_f32 v[100:101], v[182:183], v[100:101], v[174:175]
	v_pk_fma_f32 v[96:97], v[160:161], v[96:97], v[176:177]
	v_cvt_pk_bf16_f32 v100, v100, v101
	v_fmamk_f32 v84, v98, 0xba800000, v84
	v_cvt_pk_bf16_f32 v101, v96, v97
	v_cvt_pk_bf16_f32 v96, v90, v91
	v_sub_f32_e32 v91, v91, v105
	v_sub_f32_e32 v90, v90, v105
	v_pk_mul_f32 v[90:91], v[90:91], v[104:105] op_sel_hi:[1,0]
	v_cvt_pk_bf16_f32 v97, v92, v93
	v_sub_f32_e32 v93, v93, v105
	v_sub_f32_e32 v92, v92, v105
	v_pk_fma_f32 v[90:91], v[158:159], v[90:91], v[170:171]
	v_pk_mul_f32 v[92:93], v[92:93], v[104:105] op_sel_hi:[1,0]
	v_cvt_pk_bf16_f32 v102, v90, v91
	v_pk_fma_f32 v[90:91], v[30:31], v[86:87], v[34:35]
	v_pk_fma_f32 v[92:93], v[156:157], v[92:93], v[172:173]
	v_fmamk_f32 v83, v98, 0xba800000, v83
	v_cvt_pk_bf16_f32 v103, v92, v93
	global_store_dwordx4 v[110:111], v[94:97], off
	global_store_dwordx4 v[108:109], v[100:103], off
	v_cvt_pk_bf16_f32 v86, v90, v91
	v_cvt_pk_bf16_f32 v87, v88, v89
	v_sub_f32_e32 v89, v89, v105
	v_sub_f32_e32 v88, v88, v105
	v_sub_f32_e32 v91, v91, v105
	v_sub_f32_e32 v90, v90, v105
	v_fmac_f32_e32 v82, 0xba800000, v98
	v_pk_mul_f32 v[90:91], v[90:91], v[104:105] op_sel_hi:[1,0]
	v_pk_mul_f32 v[88:89], v[88:89], v[104:105] op_sel_hi:[1,0]
	v_pk_mul_f32 v[82:83], v[82:83], v[106:107] op_sel_hi:[1,0]
	v_pk_mul_f32 v[84:85], v[84:85], v[106:107] op_sel_hi:[1,0]
	v_pk_fma_f32 v[88:89], v[150:151], v[88:89], v[168:169]
	v_pk_fma_f32 v[90:91], v[152:153], v[90:91], v[166:167]
	v_pk_fma_f32 v[84:85], v[20:21], v[84:85], v[24:25]
	v_pk_fma_f32 v[82:83], v[18:19], v[82:83], v[22:23]
	v_cvt_pk_bf16_f32 v90, v90, v91
	v_cvt_pk_bf16_f32 v91, v88, v89
	v_lshl_add_u32 v112, v107, 5, 0
	v_cvt_pk_bf16_f32 v88, v82, v83
	v_cvt_pk_bf16_f32 v89, v84, v85
	v_sub_f32_e32 v85, v85, v105
	v_sub_f32_e32 v84, v84, v105
	v_sub_f32_e32 v83, v83, v105
	v_sub_f32_e32 v82, v82, v105
	v_pk_mul_f32 v[82:83], v[82:83], v[104:105] op_sel_hi:[1,0]
	v_pk_mul_f32 v[84:85], v[84:85], v[104:105] op_sel_hi:[1,0]
	v_pk_fma_f32 v[82:83], v[148:149], v[82:83], v[162:163]
	v_pk_fma_f32 v[84:85], v[146:147], v[84:85], v[164:165]
	v_cvt_pk_bf16_f32 v92, v82, v83
	s_nop 0
	v_cvt_pk_bf16_f32 v93, v84, v85
	global_store_dwordx4 v[110:111], v[86:89], off offset:256
	global_store_dwordx4 v[108:109], v[90:93], off offset:256
	ds_read_b128 v[82:85], v112 offset:24576
	ds_read_b64 v[86:87], v112 offset:24592
	s_waitcnt lgkmcnt(1)
	v_mul_f32_e32 v89, 0x3a800000, v82
	v_mov_b32_e32 v88, v83
	v_mov_b32_e32 v189, v89
	v_pk_mul_f32 v[90:91], v[88:89], v[188:189]
	s_waitcnt lgkmcnt(0)
	v_mov_b32_e32 v186, v86
	v_sub_f32_e32 v83, v90, v91
	v_add_f32_e32 v83, 0x3727c5ac, v83
	v_rsq_f32_e32 v232, v83
	v_fmamk_f32 v81, v82, 0xba800000, v81
	v_fmamk_f32 v80, v82, 0xba800000, v80
	v_fmamk_f32 v79, v82, 0xba800000, v79
	v_fmac_f32_e32 v78, 0xba800000, v82
	v_fmamk_f32 v75, v82, 0xba800000, v75
	v_fmac_f32_e32 v74, 0xba800000, v82
	v_fmamk_f32 v77, v82, 0xba800000, v77
	v_fmamk_f32 v76, v82, 0xba800000, v76
	v_add_u32_e32 v92, s26, v107
	v_ashrrev_i32_e32 v93, 31, v92
	v_lshlrev_b64 v[92:93], 11, v[92:93]
	v_fmamk_f32 v73, v82, 0xba800000, v73
	v_fmamk_f32 v72, v82, 0xba800000, v72
	v_mov_b32_e32 v90, v232
	v_mul_f32_e32 v83, v84, v90
	v_mul_f32_e32 v84, v90, v90
	v_mul_f32_e32 v191, v91, v90
	v_fma_f32 v88, v85, v84, v192
	v_pk_mul_f32 v[84:85], v[90:91], v[190:191] op_sel_hi:[0,1]
	v_pk_mul_f32 v[84:85], v[186:187], v[84:85]
	v_fmamk_f32 v71, v82, 0xba800000, v71
	v_add_f32_e32 v85, v88, v85
	v_add_f32_e32 v88, v89, v89
	v_add_f32_e32 v86, v84, v85
	v_pk_mul_f32 v[84:85], v[88:89], v[90:91] op_sel_hi:[1,0]
	v_add_u32_e32 v91, 0xa0, v1
	v_mul_f32_e32 v88, v90, v84
	v_mul_f32_e32 v87, v87, v88
	v_sub_f32_e32 v86, v86, v87
	v_add_f32_e32 v87, v83, v193
	v_pk_fma_f32 v[84:85], v[184:185], v[84:85], v[86:87] neg_lo:[1,0,0] neg_hi:[1,0,0]
	v_pk_mul_f32 v[78:79], v[78:79], v[90:91] op_sel_hi:[1,0]
	v_pk_mul_f32 v[88:89], v[84:85], s[8:9] op_sel_hi:[1,0]
	v_pk_mul_f32 v[80:81], v[80:81], v[90:91] op_sel_hi:[1,0]
	v_fma_f32 v83, -v89, v89, v88
	v_add_f32_e32 v83, 0x3727c5ac, v83
	v_rsq_f32_e32 v232, v83
	v_pk_fma_f32 v[80:81], v[40:41], v[80:81], v[48:49]
	v_pk_mul_f32 v[74:75], v[74:75], v[90:91] op_sel_hi:[1,0]
	v_lshl_add_u64 v[84:85], s[84:85], 0, v[92:93]
	v_lshl_add_u64 v[94:95], v[84:85], 0, v[154:155]
	v_lshl_add_u64 v[84:85], s[66:67], 0, v[92:93]
	v_lshl_add_u64 v[92:93], v[84:85], 0, v[154:155]
	v_pk_fma_f32 v[74:75], v[26:27], v[74:75], v[42:43]
	v_pk_mul_f32 v[76:77], v[76:77], v[90:91] op_sel_hi:[1,0]
	v_pk_fma_f32 v[76:77], v[28:29], v[76:77], v[44:45]
	v_fmac_f32_e32 v70, 0xba800000, v82
	v_pk_mul_f32 v[70:71], v[70:71], v[90:91] op_sel_hi:[1,0]
	v_pk_mul_f32 v[72:73], v[72:73], v[90:91] op_sel_hi:[1,0]
	v_fmamk_f32 v69, v82, 0xba800000, v69
	v_mov_b32_e32 v88, v232
	v_pk_fma_f32 v[84:85], v[38:39], v[78:79], v[46:47]
	v_pk_fma_f32 v[72:73], v[32:33], v[72:73], v[36:37]
	v_cvt_pk_bf16_f32 v78, v84, v85
	v_cvt_pk_bf16_f32 v79, v80, v81
	v_sub_f32_e32 v81, v81, v89
	v_sub_f32_e32 v80, v80, v89
	v_sub_f32_e32 v85, v85, v89
	v_sub_f32_e32 v84, v84, v89
	v_pk_mul_f32 v[84:85], v[84:85], v[88:89] op_sel_hi:[1,0]
	v_pk_mul_f32 v[80:81], v[80:81], v[88:89] op_sel_hi:[1,0]
	v_pk_fma_f32 v[84:85], v[182:183], v[84:85], v[174:175]
	v_pk_fma_f32 v[80:81], v[160:161], v[80:81], v[176:177]
	v_cvt_pk_bf16_f32 v84, v84, v85
	v_fmamk_f32 v68, v82, 0xba800000, v68
	v_cvt_pk_bf16_f32 v85, v80, v81
	v_cvt_pk_bf16_f32 v80, v74, v75
	v_sub_f32_e32 v75, v75, v89
	v_sub_f32_e32 v74, v74, v89
	v_pk_mul_f32 v[74:75], v[74:75], v[88:89] op_sel_hi:[1,0]
	v_cvt_pk_bf16_f32 v81, v76, v77
	v_sub_f32_e32 v77, v77, v89
	v_sub_f32_e32 v76, v76, v89
	v_pk_fma_f32 v[74:75], v[158:159], v[74:75], v[170:171]
	v_pk_mul_f32 v[76:77], v[76:77], v[88:89] op_sel_hi:[1,0]
	v_cvt_pk_bf16_f32 v86, v74, v75
	v_pk_fma_f32 v[74:75], v[30:31], v[70:71], v[34:35]
	v_pk_fma_f32 v[76:77], v[156:157], v[76:77], v[172:173]
	v_fmamk_f32 v67, v82, 0xba800000, v67
	v_cvt_pk_bf16_f32 v87, v76, v77
	global_store_dwordx4 v[94:95], v[78:81], off
	global_store_dwordx4 v[92:93], v[84:87], off
	v_cvt_pk_bf16_f32 v70, v74, v75
	v_cvt_pk_bf16_f32 v71, v72, v73
	v_sub_f32_e32 v73, v73, v89
	v_sub_f32_e32 v72, v72, v89
	v_sub_f32_e32 v75, v75, v89
	v_sub_f32_e32 v74, v74, v89
	v_fmac_f32_e32 v66, 0xba800000, v82
	v_pk_mul_f32 v[74:75], v[74:75], v[88:89] op_sel_hi:[1,0]
	v_pk_mul_f32 v[72:73], v[72:73], v[88:89] op_sel_hi:[1,0]
	v_pk_mul_f32 v[66:67], v[66:67], v[90:91] op_sel_hi:[1,0]
	v_pk_mul_f32 v[68:69], v[68:69], v[90:91] op_sel_hi:[1,0]
	v_pk_fma_f32 v[72:73], v[150:151], v[72:73], v[168:169]
	v_pk_fma_f32 v[74:75], v[152:153], v[74:75], v[166:167]
	v_pk_fma_f32 v[68:69], v[20:21], v[68:69], v[24:25]
	v_pk_fma_f32 v[66:67], v[18:19], v[66:67], v[22:23]
	v_cvt_pk_bf16_f32 v74, v74, v75
	v_cvt_pk_bf16_f32 v75, v72, v73
	v_lshl_add_u32 v96, v91, 5, 0
	v_cvt_pk_bf16_f32 v72, v66, v67
	v_cvt_pk_bf16_f32 v73, v68, v69
	v_sub_f32_e32 v69, v69, v89
	v_sub_f32_e32 v68, v68, v89
	v_sub_f32_e32 v67, v67, v89
	v_sub_f32_e32 v66, v66, v89
	v_pk_mul_f32 v[66:67], v[66:67], v[88:89] op_sel_hi:[1,0]
	v_pk_mul_f32 v[68:69], v[68:69], v[88:89] op_sel_hi:[1,0]
	v_pk_fma_f32 v[66:67], v[148:149], v[66:67], v[162:163]
	v_pk_fma_f32 v[68:69], v[146:147], v[68:69], v[164:165]
	v_cvt_pk_bf16_f32 v76, v66, v67
	v_add_u32_e32 v1, 0xb0, v1
	v_cvt_pk_bf16_f32 v77, v68, v69
	global_store_dwordx4 v[94:95], v[70:73], off offset:256
	global_store_dwordx4 v[92:93], v[74:77], off offset:256
	ds_read_b128 v[66:69], v96 offset:24576
	ds_read_b64 v[70:71], v96 offset:24592
	s_waitcnt lgkmcnt(1)
	v_mul_f32_e32 v73, 0x3a800000, v66
	v_mov_b32_e32 v72, v67
	v_mov_b32_e32 v189, v73
	v_pk_mul_f32 v[74:75], v[72:73], v[188:189]
	s_waitcnt lgkmcnt(0)
	v_mov_b32_e32 v186, v70
	v_sub_f32_e32 v67, v74, v75
	v_add_f32_e32 v67, 0x3727c5ac, v67
	v_rsq_f32_e32 v232, v67
	v_fmamk_f32 v65, v66, 0xba800000, v65
	v_fmamk_f32 v64, v66, 0xba800000, v64
	v_fmamk_f32 v63, v66, 0xba800000, v63
	v_fmac_f32_e32 v62, 0xba800000, v66
	v_fmamk_f32 v59, v66, 0xba800000, v59
	v_fmac_f32_e32 v58, 0xba800000, v66
	v_fmamk_f32 v61, v66, 0xba800000, v61
	v_fmamk_f32 v60, v66, 0xba800000, v60
	v_add_u32_e32 v76, s26, v91
	v_ashrrev_i32_e32 v77, 31, v76
	v_lshlrev_b64 v[76:77], 11, v[76:77]
	v_fmamk_f32 v57, v66, 0xba800000, v57
	v_fmamk_f32 v56, v66, 0xba800000, v56
	v_mov_b32_e32 v74, v232
	v_mul_f32_e32 v67, v68, v74
	v_mul_f32_e32 v68, v74, v74
	v_mul_f32_e32 v191, v75, v74
	v_fma_f32 v72, v69, v68, v192
	v_pk_mul_f32 v[68:69], v[74:75], v[190:191] op_sel_hi:[0,1]
	v_pk_mul_f32 v[68:69], v[186:187], v[68:69]
	v_fmamk_f32 v55, v66, 0xba800000, v55
	v_add_f32_e32 v69, v72, v69
	v_add_f32_e32 v72, v73, v73
	v_add_f32_e32 v70, v68, v69
	v_pk_mul_f32 v[68:69], v[72:73], v[74:75] op_sel_hi:[1,0]
	v_lshl_add_u32 v75, v1, 5, 0
	v_mul_f32_e32 v72, v74, v68
	v_mul_f32_e32 v71, v71, v72
	v_sub_f32_e32 v70, v70, v71
	v_add_f32_e32 v71, v67, v193
	v_pk_fma_f32 v[68:69], v[184:185], v[68:69], v[70:71] neg_lo:[1,0,0] neg_hi:[1,0,0]
	v_pk_mul_f32 v[62:63], v[62:63], v[74:75] op_sel_hi:[1,0]
	v_pk_mul_f32 v[72:73], v[68:69], s[8:9] op_sel_hi:[1,0]
	v_pk_mul_f32 v[64:65], v[64:65], v[74:75] op_sel_hi:[1,0]
	v_fma_f32 v67, -v73, v73, v72
	v_add_f32_e32 v67, 0x3727c5ac, v67
	v_rsq_f32_e32 v232, v67
	v_pk_fma_f32 v[64:65], v[40:41], v[64:65], v[48:49]
	v_pk_mul_f32 v[58:59], v[58:59], v[74:75] op_sel_hi:[1,0]
	v_lshl_add_u64 v[68:69], s[84:85], 0, v[76:77]
	v_lshl_add_u64 v[78:79], v[68:69], 0, v[154:155]
	v_lshl_add_u64 v[68:69], s[66:67], 0, v[76:77]
	v_lshl_add_u64 v[76:77], v[68:69], 0, v[154:155]
	v_pk_fma_f32 v[58:59], v[26:27], v[58:59], v[42:43]
	v_pk_mul_f32 v[60:61], v[60:61], v[74:75] op_sel_hi:[1,0]
	v_pk_fma_f32 v[60:61], v[28:29], v[60:61], v[44:45]
	v_fmac_f32_e32 v54, 0xba800000, v66
	v_pk_mul_f32 v[54:55], v[54:55], v[74:75] op_sel_hi:[1,0]
	v_pk_mul_f32 v[56:57], v[56:57], v[74:75] op_sel_hi:[1,0]
	v_fmamk_f32 v53, v66, 0xba800000, v53
	v_mov_b32_e32 v72, v232
	v_pk_fma_f32 v[68:69], v[38:39], v[62:63], v[46:47]
	v_pk_fma_f32 v[56:57], v[32:33], v[56:57], v[36:37]
	v_cvt_pk_bf16_f32 v62, v68, v69
	v_cvt_pk_bf16_f32 v63, v64, v65
	v_sub_f32_e32 v65, v65, v73
	v_sub_f32_e32 v64, v64, v73
	v_sub_f32_e32 v69, v69, v73
	v_sub_f32_e32 v68, v68, v73
	v_pk_mul_f32 v[68:69], v[68:69], v[72:73] op_sel_hi:[1,0]
	v_pk_mul_f32 v[64:65], v[64:65], v[72:73] op_sel_hi:[1,0]
	v_pk_fma_f32 v[68:69], v[182:183], v[68:69], v[174:175]
	v_pk_fma_f32 v[64:65], v[160:161], v[64:65], v[176:177]
	v_cvt_pk_bf16_f32 v68, v68, v69
	v_fmamk_f32 v52, v66, 0xba800000, v52
	v_cvt_pk_bf16_f32 v69, v64, v65
	v_cvt_pk_bf16_f32 v64, v58, v59
	v_sub_f32_e32 v59, v59, v73
	v_sub_f32_e32 v58, v58, v73
	v_pk_mul_f32 v[58:59], v[58:59], v[72:73] op_sel_hi:[1,0]
	v_cvt_pk_bf16_f32 v65, v60, v61
	v_sub_f32_e32 v61, v61, v73
	v_sub_f32_e32 v60, v60, v73
	v_pk_fma_f32 v[58:59], v[158:159], v[58:59], v[170:171]
	v_pk_mul_f32 v[60:61], v[60:61], v[72:73] op_sel_hi:[1,0]
	v_cvt_pk_bf16_f32 v70, v58, v59
	v_pk_fma_f32 v[58:59], v[30:31], v[54:55], v[34:35]
	v_pk_fma_f32 v[60:61], v[156:157], v[60:61], v[172:173]
	v_fmamk_f32 v51, v66, 0xba800000, v51
	v_cvt_pk_bf16_f32 v71, v60, v61
	global_store_dwordx4 v[78:79], v[62:65], off
	global_store_dwordx4 v[76:77], v[68:71], off
	v_cvt_pk_bf16_f32 v54, v58, v59
	v_cvt_pk_bf16_f32 v55, v56, v57
	v_sub_f32_e32 v57, v57, v73
	v_sub_f32_e32 v56, v56, v73
	v_sub_f32_e32 v59, v59, v73
	v_sub_f32_e32 v58, v58, v73
	v_fmac_f32_e32 v50, 0xba800000, v66
	v_pk_mul_f32 v[58:59], v[58:59], v[72:73] op_sel_hi:[1,0]
	v_pk_mul_f32 v[56:57], v[56:57], v[72:73] op_sel_hi:[1,0]
	v_pk_mul_f32 v[50:51], v[50:51], v[74:75] op_sel_hi:[1,0]
	v_pk_mul_f32 v[52:53], v[52:53], v[74:75] op_sel_hi:[1,0]
	v_pk_fma_f32 v[56:57], v[150:151], v[56:57], v[168:169]
	v_pk_fma_f32 v[58:59], v[152:153], v[58:59], v[166:167]
	v_pk_fma_f32 v[52:53], v[20:21], v[52:53], v[24:25]
	v_pk_fma_f32 v[50:51], v[18:19], v[50:51], v[22:23]
	v_cvt_pk_bf16_f32 v58, v58, v59
	v_cvt_pk_bf16_f32 v59, v56, v57
	s_nop 0
	v_cvt_pk_bf16_f32 v56, v50, v51
	v_cvt_pk_bf16_f32 v57, v52, v53
	v_sub_f32_e32 v53, v53, v73
	v_sub_f32_e32 v52, v52, v73
	v_sub_f32_e32 v51, v51, v73
	v_sub_f32_e32 v50, v50, v73
	v_pk_mul_f32 v[50:51], v[50:51], v[72:73] op_sel_hi:[1,0]
	v_pk_mul_f32 v[52:53], v[52:53], v[72:73] op_sel_hi:[1,0]
	v_pk_fma_f32 v[50:51], v[148:149], v[50:51], v[162:163]
	v_pk_fma_f32 v[52:53], v[146:147], v[52:53], v[164:165]
	v_cvt_pk_bf16_f32 v60, v50, v51
	s_nop 0
	v_cvt_pk_bf16_f32 v61, v52, v53
	global_store_dwordx4 v[78:79], v[54:57], off offset:256
	global_store_dwordx4 v[76:77], v[58:61], off offset:256
	ds_read_b128 v[50:53], v75 offset:24576
	ds_read_b64 v[54:55], v75 offset:24592
	s_waitcnt lgkmcnt(1)
	v_mul_f32_e32 v57, 0x3a800000, v50
	v_mov_b32_e32 v56, v51
	v_mov_b32_e32 v189, v57
	v_pk_mul_f32 v[58:59], v[56:57], v[188:189]
	s_waitcnt lgkmcnt(0)
	v_mov_b32_e32 v186, v54
	v_sub_f32_e32 v56, v58, v59
	v_add_f32_e32 v56, 0x3727c5ac, v56
	v_rsq_f32_e32 v232, v56
	v_fmamk_f32 v17, v50, 0xba800000, v17
	v_fmamk_f32 v16, v50, 0xba800000, v16
	v_fmamk_f32 v15, v50, 0xba800000, v15
	v_fmac_f32_e32 v14, 0xba800000, v50
	v_fmamk_f32 v11, v50, 0xba800000, v11
	v_fmac_f32_e32 v10, 0xba800000, v50
	v_fmamk_f32 v13, v50, 0xba800000, v13
	v_fmamk_f32 v12, v50, 0xba800000, v12
	v_mov_b32_e32 v60, v51
	v_mov_b32_e32 v61, v52
	v_fmamk_f32 v9, v50, 0xba800000, v9
	v_fmamk_f32 v8, v50, 0xba800000, v8
	v_fmamk_f32 v7, v50, 0xba800000, v7
	v_mov_b32_e32 v58, v232
	v_mul_f32_e32 v191, v59, v58
	v_mul_f32_e32 v51, v58, v58
	v_pk_mul_f32 v[62:63], v[58:59], v[190:191] op_sel_hi:[0,1]
	v_fmac_f32_e32 v192, v53, v51
	v_pk_mul_f32 v[62:63], v[186:187], v[62:63]
	v_add_f32_e32 v56, v57, v57
	v_add_f32_e32 v51, v192, v63
	v_pk_mul_f32 v[56:57], v[56:57], v[58:59] op_sel_hi:[1,0]
	v_add_f32_e32 v192, v62, v51
	v_mul_f32_e32 v54, v58, v56
	v_mov_b32_e32 v62, v55
	v_mov_b32_e32 v63, v52
	v_mov_b32_e32 v55, v58
	v_pk_fma_f32 v[52:53], v[62:63], v[54:55], v[192:193] neg_lo:[1,0,0] neg_hi:[1,0,0]
	v_pk_fma_f32 v[54:55], v[60:61], v[58:59], v[192:193] op_sel_hi:[1,0,1]
	v_pk_mul_f32 v[14:15], v[14:15], v[58:59] op_sel_hi:[1,0]
	v_mov_b32_e32 v53, v55
	v_pk_fma_f32 v[52:53], v[184:185], v[56:57], v[52:53] neg_lo:[1,0,0] neg_hi:[1,0,0]
	v_pk_mul_f32 v[16:17], v[16:17], v[58:59] op_sel_hi:[1,0]
	v_pk_mul_f32 v[52:53], v[52:53], s[8:9] op_sel_hi:[1,0]
	v_pk_fma_f32 v[16:17], v[40:41], v[16:17], v[48:49]
	v_fma_f32 v51, -v53, v53, v52
	v_add_f32_e32 v51, 0x3727c5ac, v51
	v_rsq_f32_e32 v232, v51
	v_pk_fma_f32 v[38:39], v[38:39], v[14:15], v[46:47]
	v_pk_mul_f32 v[10:11], v[10:11], v[58:59] op_sel_hi:[1,0]
	v_cvt_pk_bf16_f32 v14, v38, v39
	v_cvt_pk_bf16_f32 v15, v16, v17
	v_sub_f32_e32 v17, v17, v53
	v_sub_f32_e32 v16, v16, v53
	v_sub_f32_e32 v39, v39, v53
	v_sub_f32_e32 v38, v38, v53
	v_pk_fma_f32 v[10:11], v[26:27], v[10:11], v[42:43]
	v_pk_mul_f32 v[12:13], v[12:13], v[58:59] op_sel_hi:[1,0]
	v_pk_fma_f32 v[12:13], v[28:29], v[12:13], v[44:45]
	v_fmac_f32_e32 v6, 0xba800000, v50
	v_pk_mul_f32 v[6:7], v[6:7], v[58:59] op_sel_hi:[1,0]
	v_mov_b32_e32 v52, v232
	v_pk_mul_f32 v[38:39], v[38:39], v[52:53] op_sel_hi:[1,0]
	v_pk_mul_f32 v[16:17], v[16:17], v[52:53] op_sel_hi:[1,0]
	v_pk_fma_f32 v[38:39], v[182:183], v[38:39], v[174:175]
	v_pk_fma_f32 v[16:17], v[160:161], v[16:17], v[176:177]
	v_add_u32_e32 v54, s26, v1
	v_cvt_pk_bf16_f32 v38, v38, v39
	v_cvt_pk_bf16_f32 v39, v16, v17
	v_cvt_pk_bf16_f32 v16, v10, v11
	v_sub_f32_e32 v11, v11, v53
	v_sub_f32_e32 v10, v10, v53
	v_ashrrev_i32_e32 v55, 31, v54
	v_pk_mul_f32 v[10:11], v[10:11], v[52:53] op_sel_hi:[1,0]
	v_lshlrev_b64 v[54:55], 11, v[54:55]
	v_pk_fma_f32 v[10:11], v[158:159], v[10:11], v[170:171]
	v_cvt_pk_bf16_f32 v17, v12, v13
	v_sub_f32_e32 v13, v13, v53
	v_sub_f32_e32 v12, v12, v53
	v_cvt_pk_bf16_f32 v40, v10, v11
	v_lshl_add_u64 v[10:11], s[84:85], 0, v[54:55]
	v_pk_mul_f32 v[12:13], v[12:13], v[52:53] op_sel_hi:[1,0]
	v_lshl_add_u64 v[26:27], v[10:11], 0, v[154:155]
	v_lshl_add_u64 v[10:11], s[66:67], 0, v[54:55]
	v_pk_mul_f32 v[8:9], v[8:9], v[58:59] op_sel_hi:[1,0]
	v_pk_fma_f32 v[12:13], v[156:157], v[12:13], v[172:173]
	v_pk_fma_f32 v[8:9], v[32:33], v[8:9], v[36:37]
	v_cvt_pk_bf16_f32 v41, v12, v13
	global_store_dwordx4 v[26:27], v[14:17], off
	v_fmamk_f32 v5, v50, 0xba800000, v5
	v_fmamk_f32 v4, v50, 0xba800000, v4
	v_lshl_add_u64 v[14:15], v[10:11], 0, v[154:155]
	v_pk_fma_f32 v[10:11], v[30:31], v[6:7], v[34:35]
	global_store_dwordx4 v[14:15], v[38:41], off
	v_cvt_pk_bf16_f32 v6, v10, v11
	v_cvt_pk_bf16_f32 v7, v8, v9
	v_sub_f32_e32 v9, v9, v53
	v_sub_f32_e32 v8, v8, v53
	v_sub_f32_e32 v11, v11, v53
	v_sub_f32_e32 v10, v10, v53
	v_fmamk_f32 v3, v50, 0xba800000, v3
	v_fmac_f32_e32 v2, 0xba800000, v50
	v_pk_mul_f32 v[10:11], v[10:11], v[52:53] op_sel_hi:[1,0]
	v_pk_mul_f32 v[8:9], v[8:9], v[52:53] op_sel_hi:[1,0]
	v_pk_mul_f32 v[2:3], v[2:3], v[58:59] op_sel_hi:[1,0]
	v_pk_mul_f32 v[4:5], v[4:5], v[58:59] op_sel_hi:[1,0]
	v_pk_fma_f32 v[8:9], v[150:151], v[8:9], v[168:169]
	v_pk_fma_f32 v[10:11], v[152:153], v[10:11], v[166:167]
	v_pk_fma_f32 v[4:5], v[20:21], v[4:5], v[24:25]
	v_pk_fma_f32 v[2:3], v[18:19], v[2:3], v[22:23]
	v_cvt_pk_bf16_f32 v10, v10, v11
	v_cvt_pk_bf16_f32 v11, v8, v9
	s_nop 0
	v_cvt_pk_bf16_f32 v8, v2, v3
	v_cvt_pk_bf16_f32 v9, v4, v5
	v_sub_f32_e32 v5, v5, v53
	v_sub_f32_e32 v4, v4, v53
	v_sub_f32_e32 v3, v3, v53
	v_sub_f32_e32 v2, v2, v53
	v_pk_mul_f32 v[2:3], v[2:3], v[52:53] op_sel_hi:[1,0]
	v_pk_mul_f32 v[4:5], v[4:5], v[52:53] op_sel_hi:[1,0]
	v_pk_fma_f32 v[2:3], v[148:149], v[2:3], v[162:163]
	v_pk_fma_f32 v[4:5], v[146:147], v[4:5], v[164:165]
	v_cvt_pk_bf16_f32 v12, v2, v3
	s_nop 0
	v_cvt_pk_bf16_f32 v13, v4, v5
	global_store_dwordx4 v[26:27], v[6:9], off offset:256
	global_store_dwordx4 v[14:15], v[10:13], off offset:256
